# QKV GEMM epilogue: ssq loads for all 8 row groups hoisted to the top, rope table rows prefetched one row group ahead into spare fragment registers (removes 8 serialized load latencies per tile)
# baseline (speedup 1.0000x reference)
.LBB0_186:
	s_cmp_lt_i32 s34, 8
	s_cselect_b64 s[12:13], -1, 0
	s_lshl_b32 s25, s10, 8
	v_add_u32_e32 v184, s25, v155
	v_ashrrev_i32_e32 v185, 31, v184
	v_lshl_add_u64 v[42:43], v[184:185], 3, s[68:69]
	global_load_dwordx2 v[186:187], v[42:43], off
	v_add_u32_e32 v240, s25, v189
	v_ashrrev_i32_e32 v241, 31, v240
	v_lshl_add_u64 v[240:241], v[240:241], 3, s[68:69]
	global_load_dwordx2 v[210:211], v[240:241], off
	v_add_u32_e32 v240, s25, v190
	v_ashrrev_i32_e32 v241, 31, v240
	v_lshl_add_u64 v[240:241], v[240:241], 3, s[68:69]
	global_load_dwordx2 v[212:213], v[240:241], off
	v_add_u32_e32 v240, s25, v191
	v_ashrrev_i32_e32 v241, 31, v240
	v_lshl_add_u64 v[240:241], v[240:241], 3, s[68:69]
	global_load_dwordx2 v[214:215], v[240:241], off
	v_add_u32_e32 v240, 0x80, v184
	v_ashrrev_i32_e32 v241, 31, v240
	v_lshl_add_u64 v[240:241], v[240:241], 3, s[68:69]
	global_load_dwordx2 v[216:217], v[240:241], off
	v_add_u32_e32 v240, 0x90, v184
	v_ashrrev_i32_e32 v241, 31, v240
	v_lshl_add_u64 v[240:241], v[240:241], 3, s[68:69]
	global_load_dwordx2 v[218:219], v[240:241], off
	v_add_u32_e32 v240, 0xa0, v184
	v_ashrrev_i32_e32 v241, 31, v240
	v_lshl_add_u64 v[240:241], v[240:241], 3, s[68:69]
	global_load_dwordx2 v[220:221], v[240:241], off
	v_add_u32_e32 v240, 0xb0, v184
	v_ashrrev_i32_e32 v241, 31, v240
	v_lshl_add_u64 v[240:241], v[240:241], 3, s[68:69]
	global_load_dwordx2 v[222:223], v[240:241], off
	s_and_b64 s[12:13], s[22:23], s[12:13]
	v_cndmask_b32_e64 v0, 0, 1, s[12:13]
	v_cmp_ne_u32_e64 s[10:11], 1, v0
	s_andn2_b64 vcc, exec, s[12:13]
	s_cbranch_vccnz .LBB0_188
	v_lshlrev_b32_e32 v0, 6, v184
	v_and_b32_e32 v0, 0x3f3c0, v0
	global_load_dwordx4 v[58:61], v0, s[38:39] offset:32
	global_load_dwordx4 v[70:73], v0, s[38:39] offset:48
	global_load_dwordx4 v[42:45], v0, s[38:39] offset:16
	global_load_dwordx4 v[54:57], v0, s[38:39]
	v_add_u32_e32 v240, s25, v189
	v_lshlrev_b32_e32 v240, 6, v240
	v_and_b32_e32 v240, 0x3f7c0, v240
	global_load_dwordx4 v[224:227], v240, s[38:39] offset:32
	global_load_dwordx4 v[228:231], v240, s[38:39] offset:48
	global_load_dwordx4 v[232:235], v240, s[38:39] offset:16
	global_load_dwordx4 v[236:239], v240, s[38:39]
	s_waitcnt vmcnt(4)
	v_xor_b32_e32 v0, 0x80000000, v58
	v_xor_b32_e32 v185, 0x80000000, v59
	v_xor_b32_e32 v193, 0x80000000, v60
	v_xor_b32_e32 v200, 0x80000000, v61
	v_xor_b32_e32 v201, 0x80000000, v70
	v_xor_b32_e32 v202, 0x80000000, v71
	v_xor_b32_e32 v203, 0x80000000, v72
	v_xor_b32_e32 v204, 0x80000000, v73
	v_cndmask_b32_e64 v61, v61, v200, s[6:7]
	v_cndmask_b32_e64 v60, v60, v193, s[6:7]
	v_cndmask_b32_e64 v59, v59, v185, s[6:7]
	v_cndmask_b32_e64 v58, v58, v0, s[6:7]
	v_cndmask_b32_e64 v73, v73, v204, s[6:7]
	v_cndmask_b32_e64 v72, v72, v203, s[6:7]
	v_cndmask_b32_e64 v71, v71, v202, s[6:7]
	v_cndmask_b32_e64 v70, v70, v201, s[6:7]
.LBB0_188:
	s_waitcnt vmcnt(4)
	v_ffbh_u32_e32 v0, v187
	v_min_u32_e32 v0, 32, v0
	v_lshlrev_b64 v[186:187], v0, v[186:187]
	v_min_u32_e32 v185, 1, v186
	v_or_b32_e32 v185, v187, v185
	v_cvt_f32_u32_e32 v185, v185
	v_sub_u32_e32 v0, 32, v0
	s_cmp_lt_u32 s34, 4
	s_cselect_b64 vcc, -1, 0
	v_ldexp_f32 v0, v185, v0
	v_mul_f32_e32 v0, 0x37800000, v0
	v_fmamk_f32 v0, v0, 0x3a800000, v195
	v_rsq_f32_e32 v0, v0
	v_cndmask_b32_e32 v185, 1.0, v197, vcc
	s_and_b64 vcc, exec, s[10:11]
	v_mul_f32_e32 v186, v185, v0
	v_pk_mul_f32 v[144:145], v[144:145], v[186:187] op_sel_hi:[1,0]
	v_pk_mul_f32 v[142:143], v[142:143], v[186:187] op_sel_hi:[1,0]
	v_pk_mul_f32 v[140:141], v[140:141], v[186:187] op_sel_hi:[1,0]
	v_pk_mul_f32 v[138:139], v[138:139], v[186:187] op_sel_hi:[1,0]
	s_cbranch_vccnz .LBB0_190
	v_mov_b32_e32 v0, v142
	v_mov_b32_e32 v187, v142
	s_nop 1
	v_permlane16_swap_b32_e32 v0, v187
	v_cndmask_b32_e64 v200, v0, v187, s[2:3]
	v_mov_b32_e32 v0, v143
	v_mov_b32_e32 v187, v143
	s_nop 1
	v_permlane16_swap_b32_e32 v0, v187
	v_cndmask_b32_e64 v201, v0, v187, s[2:3]
	v_mov_b32_e32 v0, v144
	v_mov_b32_e32 v187, v144
	s_nop 1
	v_permlane16_swap_b32_e32 v0, v187
	v_cndmask_b32_e64 v202, v0, v187, s[2:3]
	v_mov_b32_e32 v0, v145
	v_mov_b32_e32 v187, v145
	s_nop 1
	v_permlane16_swap_b32_e32 v0, v187
	v_cndmask_b32_e64 v203, v0, v187, s[2:3]
	v_mov_b32_e32 v0, v138
	v_mov_b32_e32 v187, v138
	s_nop 1
	v_permlane16_swap_b32_e32 v0, v187
	v_cndmask_b32_e64 v204, v0, v187, s[2:3]
	v_mov_b32_e32 v0, v139
	v_mov_b32_e32 v187, v139
	s_nop 1
	v_permlane16_swap_b32_e32 v0, v187
	v_cndmask_b32_e64 v205, v0, v187, s[2:3]
	v_mov_b32_e32 v0, v140
	v_mov_b32_e32 v187, v140
	s_nop 1
	v_permlane16_swap_b32_e32 v0, v187
	v_cndmask_b32_e64 v206, v0, v187, s[2:3]
	v_mov_b32_e32 v0, v141
	v_mov_b32_e32 v187, v141
	s_nop 1
	v_permlane16_swap_b32_e32 v0, v187
	v_cndmask_b32_e64 v207, v0, v187, s[2:3]
	v_pk_mul_f32 v[202:203], v[60:61], v[202:203]
	v_pk_mul_f32 v[200:201], v[58:59], v[200:201]
	v_pk_mul_f32 v[206:207], v[72:73], v[206:207]
	v_pk_mul_f32 v[204:205], v[70:71], v[204:205]
	v_pk_fma_f32 v[200:201], v[142:143], v[54:55], v[200:201]
	v_pk_fma_f32 v[202:203], v[144:145], v[56:57], v[202:203]
	v_pk_fma_f32 v[204:205], v[138:139], v[42:43], v[204:205]
	v_pk_fma_f32 v[206:207], v[140:141], v[44:45], v[206:207]
	v_cndmask_b32_e64 v145, v145, v203, s[4:5]
	v_cndmask_b32_e64 v144, v144, v202, s[4:5]
	v_cndmask_b32_e64 v143, v143, v201, s[4:5]
	v_cndmask_b32_e64 v142, v142, v200, s[4:5]
	v_cndmask_b32_e64 v141, v141, v207, s[4:5]
	v_cndmask_b32_e64 v140, v140, v206, s[4:5]
	v_cndmask_b32_e64 v139, v139, v205, s[4:5]
	v_cndmask_b32_e64 v138, v138, v204, s[4:5]

.LBB0_192:
	v_cvt_pk_bf16_f32 v134, v134, v135
	v_cvt_pk_bf16_f32 v135, v136, v137
	v_cvt_pk_bf16_f32 v136, v130, v131
	v_cvt_pk_bf16_f32 v137, v132, v133
	v_add_u32_e32 v130, s25, v189
	global_store_dwordx4 v[138:139], v[134:137], off offset:256
	v_ashrrev_i32_e32 v131, 31, v130
	s_waitcnt vmcnt(2)
	v_mov_b64_e32 v[132:133], v[210:211]
	s_and_b64 vcc, exec, s[10:11]
	s_cbranch_vccnz .LBB0_194
	v_mov_b64_e32 v[58:59], v[224:225]
	v_mov_b64_e32 v[60:61], v[226:227]
	v_mov_b64_e32 v[70:71], v[228:229]
	v_mov_b64_e32 v[72:73], v[230:231]
	v_mov_b64_e32 v[42:43], v[232:233]
	v_mov_b64_e32 v[44:45], v[234:235]
	v_mov_b64_e32 v[54:55], v[236:237]
	v_mov_b64_e32 v[56:57], v[238:239]
	v_add_u32_e32 v240, s25, v190
	v_lshlrev_b32_e32 v240, 6, v240
	v_and_b32_e32 v240, 0x3fbc0, v240
	global_load_dwordx4 v[224:227], v240, s[38:39] offset:32
	global_load_dwordx4 v[228:231], v240, s[38:39] offset:48
	global_load_dwordx4 v[232:235], v240, s[38:39] offset:16
	global_load_dwordx4 v[236:239], v240, s[38:39]
	v_xor_b32_e32 v131, 0x80000000, v58
	v_xor_b32_e32 v134, 0x80000000, v59
	v_xor_b32_e32 v135, 0x80000000, v60
	v_xor_b32_e32 v136, 0x80000000, v61
	v_xor_b32_e32 v137, 0x80000000, v70
	v_xor_b32_e32 v138, 0x80000000, v71
	v_xor_b32_e32 v139, 0x80000000, v72
	v_xor_b32_e32 v140, 0x80000000, v73
	v_cndmask_b32_e64 v61, v61, v136, s[6:7]
	v_cndmask_b32_e64 v60, v60, v135, s[6:7]
	v_cndmask_b32_e64 v59, v59, v134, s[6:7]
	v_cndmask_b32_e64 v58, v58, v131, s[6:7]
	v_cndmask_b32_e64 v73, v73, v140, s[6:7]
	v_cndmask_b32_e64 v72, v72, v139, s[6:7]
	v_cndmask_b32_e64 v71, v71, v138, s[6:7]
	v_cndmask_b32_e64 v70, v70, v137, s[6:7]
.LBB0_194:
	v_ffbh_u32_e32 v131, v133
	v_min_u32_e32 v131, 32, v131
	v_lshlrev_b64 v[132:133], v131, v[132:133]
	v_min_u32_e32 v132, 1, v132
	v_or_b32_e32 v132, v133, v132
	v_cvt_f32_u32_e32 v132, v132
	v_sub_u32_e32 v131, 32, v131
	s_and_b64 vcc, exec, s[10:11]
	v_ldexp_f32 v131, v132, v131
	v_mul_f32_e32 v131, 0x37800000, v131
	v_fmamk_f32 v131, v131, 0x3a800000, v195
	v_rsq_f32_e32 v131, v131
	s_nop 0
	v_mul_f32_e32 v132, v185, v131
	v_pk_mul_f32 v[128:129], v[128:129], v[132:133] op_sel_hi:[1,0]
	v_pk_mul_f32 v[126:127], v[126:127], v[132:133] op_sel_hi:[1,0]
	v_pk_mul_f32 v[124:125], v[124:125], v[132:133] op_sel_hi:[1,0]
	v_pk_mul_f32 v[122:123], v[122:123], v[132:133] op_sel_hi:[1,0]
	s_cbranch_vccnz .LBB0_196
	v_mov_b32_e32 v131, v126
	v_mov_b32_e32 v133, v126
	s_nop 1
	v_permlane16_swap_b32_e32 v131, v133
	v_cndmask_b32_e64 v134, v131, v133, s[2:3]
	v_mov_b32_e32 v131, v127
	v_mov_b32_e32 v133, v127
	s_nop 1
	v_permlane16_swap_b32_e32 v131, v133
	v_cndmask_b32_e64 v135, v131, v133, s[2:3]
	v_mov_b32_e32 v131, v128
	v_mov_b32_e32 v133, v128
	s_nop 1
	v_permlane16_swap_b32_e32 v131, v133
	v_cndmask_b32_e64 v136, v131, v133, s[2:3]
	v_mov_b32_e32 v131, v129
	v_mov_b32_e32 v133, v129
	s_nop 1
	v_permlane16_swap_b32_e32 v131, v133
	v_cndmask_b32_e64 v137, v131, v133, s[2:3]
	v_mov_b32_e32 v131, v122
	v_mov_b32_e32 v133, v122
	s_nop 1
	v_permlane16_swap_b32_e32 v131, v133
	v_cndmask_b32_e64 v138, v131, v133, s[2:3]
	v_mov_b32_e32 v131, v123
	v_mov_b32_e32 v133, v123
	s_nop 1
	v_permlane16_swap_b32_e32 v131, v133
	v_cndmask_b32_e64 v139, v131, v133, s[2:3]
	v_mov_b32_e32 v131, v124
	v_mov_b32_e32 v133, v124
	s_nop 1
	v_permlane16_swap_b32_e32 v131, v133
	v_cndmask_b32_e64 v140, v131, v133, s[2:3]
	v_mov_b32_e32 v131, v125
	v_mov_b32_e32 v133, v125
	s_nop 1
	v_permlane16_swap_b32_e32 v131, v133
	v_cndmask_b32_e64 v141, v131, v133, s[2:3]
	v_pk_mul_f32 v[136:137], v[60:61], v[136:137]
	v_pk_mul_f32 v[134:135], v[58:59], v[134:135]
	v_pk_mul_f32 v[140:141], v[72:73], v[140:141]
	v_pk_mul_f32 v[138:139], v[70:71], v[138:139]
	v_pk_fma_f32 v[134:135], v[126:127], v[54:55], v[134:135]
	v_pk_fma_f32 v[136:137], v[128:129], v[56:57], v[136:137]
	v_pk_fma_f32 v[138:139], v[122:123], v[42:43], v[138:139]
	v_pk_fma_f32 v[140:141], v[124:125], v[44:45], v[140:141]
	v_cndmask_b32_e64 v129, v129, v137, s[4:5]
	v_cndmask_b32_e64 v128, v128, v136, s[4:5]
	v_cndmask_b32_e64 v127, v127, v135, s[4:5]
	v_cndmask_b32_e64 v126, v126, v134, s[4:5]
	v_cndmask_b32_e64 v125, v125, v141, s[4:5]
	v_cndmask_b32_e64 v124, v124, v140, s[4:5]
	v_cndmask_b32_e64 v123, v123, v139, s[4:5]
	v_cndmask_b32_e64 v122, v122, v138, s[4:5]

.LBB0_198:
	v_cvt_pk_bf16_f32 v118, v118, v119
	v_cvt_pk_bf16_f32 v119, v120, v121
	v_cvt_pk_bf16_f32 v120, v114, v115
	v_cvt_pk_bf16_f32 v121, v116, v117
	v_add_u32_e32 v114, s25, v190
	global_store_dwordx4 v[122:123], v[118:121], off offset:256
	v_ashrrev_i32_e32 v115, 31, v114
	s_waitcnt vmcnt(2)
	v_mov_b64_e32 v[116:117], v[212:213]
	s_and_b64 vcc, exec, s[10:11]
	s_cbranch_vccnz .LBB0_200
	v_mov_b64_e32 v[58:59], v[224:225]
	v_mov_b64_e32 v[60:61], v[226:227]
	v_mov_b64_e32 v[70:71], v[228:229]
	v_mov_b64_e32 v[72:73], v[230:231]
	v_mov_b64_e32 v[42:43], v[232:233]
	v_mov_b64_e32 v[44:45], v[234:235]
	v_mov_b64_e32 v[54:55], v[236:237]
	v_mov_b64_e32 v[56:57], v[238:239]
	v_add_u32_e32 v240, s25, v191
	v_lshlrev_b32_e32 v240, 6, v240
	v_and_b32_e32 v240, 0x3ffc0, v240
	global_load_dwordx4 v[224:227], v240, s[38:39] offset:32
	global_load_dwordx4 v[228:231], v240, s[38:39] offset:48
	global_load_dwordx4 v[232:235], v240, s[38:39] offset:16
	global_load_dwordx4 v[236:239], v240, s[38:39]
	v_xor_b32_e32 v115, 0x80000000, v58
	v_xor_b32_e32 v118, 0x80000000, v59
	v_xor_b32_e32 v119, 0x80000000, v60
	v_xor_b32_e32 v120, 0x80000000, v61
	v_xor_b32_e32 v121, 0x80000000, v70
	v_xor_b32_e32 v122, 0x80000000, v71
	v_xor_b32_e32 v123, 0x80000000, v72
	v_xor_b32_e32 v124, 0x80000000, v73
	v_cndmask_b32_e64 v61, v61, v120, s[6:7]
	v_cndmask_b32_e64 v60, v60, v119, s[6:7]
	v_cndmask_b32_e64 v59, v59, v118, s[6:7]
	v_cndmask_b32_e64 v58, v58, v115, s[6:7]
	v_cndmask_b32_e64 v73, v73, v124, s[6:7]
	v_cndmask_b32_e64 v72, v72, v123, s[6:7]
	v_cndmask_b32_e64 v71, v71, v122, s[6:7]
	v_cndmask_b32_e64 v70, v70, v121, s[6:7]
.LBB0_200:
	v_ffbh_u32_e32 v115, v117
	v_min_u32_e32 v115, 32, v115
	v_lshlrev_b64 v[116:117], v115, v[116:117]
	v_min_u32_e32 v116, 1, v116
	v_or_b32_e32 v116, v117, v116
	v_cvt_f32_u32_e32 v116, v116
	v_sub_u32_e32 v115, 32, v115
	s_and_b64 vcc, exec, s[10:11]
	v_ldexp_f32 v115, v116, v115
	v_mul_f32_e32 v115, 0x37800000, v115
	v_fmamk_f32 v115, v115, 0x3a800000, v195
	v_rsq_f32_e32 v115, v115
	s_nop 0
	v_mul_f32_e32 v116, v185, v115
	v_pk_mul_f32 v[112:113], v[112:113], v[116:117] op_sel_hi:[1,0]
	v_pk_mul_f32 v[110:111], v[110:111], v[116:117] op_sel_hi:[1,0]
	v_pk_mul_f32 v[108:109], v[108:109], v[116:117] op_sel_hi:[1,0]
	v_pk_mul_f32 v[106:107], v[106:107], v[116:117] op_sel_hi:[1,0]
	s_cbranch_vccnz .LBB0_202
	v_mov_b32_e32 v115, v110
	v_mov_b32_e32 v117, v110
	s_nop 1
	v_permlane16_swap_b32_e32 v115, v117
	v_cndmask_b32_e64 v118, v115, v117, s[2:3]
	v_mov_b32_e32 v115, v111
	v_mov_b32_e32 v117, v111
	s_nop 1
	v_permlane16_swap_b32_e32 v115, v117
	v_cndmask_b32_e64 v119, v115, v117, s[2:3]
	v_mov_b32_e32 v115, v112
	v_mov_b32_e32 v117, v112
	s_nop 1
	v_permlane16_swap_b32_e32 v115, v117
	v_cndmask_b32_e64 v120, v115, v117, s[2:3]
	v_mov_b32_e32 v115, v113
	v_mov_b32_e32 v117, v113
	s_nop 1
	v_permlane16_swap_b32_e32 v115, v117
	v_cndmask_b32_e64 v121, v115, v117, s[2:3]
	v_mov_b32_e32 v115, v106
	v_mov_b32_e32 v117, v106
	s_nop 1
	v_permlane16_swap_b32_e32 v115, v117
	v_cndmask_b32_e64 v122, v115, v117, s[2:3]
	v_mov_b32_e32 v115, v107
	v_mov_b32_e32 v117, v107
	s_nop 1
	v_permlane16_swap_b32_e32 v115, v117
	v_cndmask_b32_e64 v123, v115, v117, s[2:3]
	v_mov_b32_e32 v115, v108
	v_mov_b32_e32 v117, v108
	s_nop 1
	v_permlane16_swap_b32_e32 v115, v117
	v_cndmask_b32_e64 v124, v115, v117, s[2:3]
	v_mov_b32_e32 v115, v109
	v_mov_b32_e32 v117, v109
	s_nop 1
	v_permlane16_swap_b32_e32 v115, v117
	v_cndmask_b32_e64 v125, v115, v117, s[2:3]
	v_pk_mul_f32 v[120:121], v[60:61], v[120:121]
	v_pk_mul_f32 v[118:119], v[58:59], v[118:119]
	v_pk_mul_f32 v[124:125], v[72:73], v[124:125]
	v_pk_mul_f32 v[122:123], v[70:71], v[122:123]
	v_pk_fma_f32 v[118:119], v[110:111], v[54:55], v[118:119]
	v_pk_fma_f32 v[120:121], v[112:113], v[56:57], v[120:121]
	v_pk_fma_f32 v[122:123], v[106:107], v[42:43], v[122:123]
	v_pk_fma_f32 v[124:125], v[108:109], v[44:45], v[124:125]
	v_cndmask_b32_e64 v113, v113, v121, s[4:5]
	v_cndmask_b32_e64 v112, v112, v120, s[4:5]
	v_cndmask_b32_e64 v111, v111, v119, s[4:5]
	v_cndmask_b32_e64 v110, v110, v118, s[4:5]
	v_cndmask_b32_e64 v109, v109, v125, s[4:5]
	v_cndmask_b32_e64 v108, v108, v124, s[4:5]
	v_cndmask_b32_e64 v107, v107, v123, s[4:5]
	v_cndmask_b32_e64 v106, v106, v122, s[4:5]

.LBB0_204:
	v_cvt_pk_bf16_f32 v102, v102, v103
	v_cvt_pk_bf16_f32 v103, v104, v105
	v_cvt_pk_bf16_f32 v104, v98, v99
	v_cvt_pk_bf16_f32 v105, v100, v101
	v_add_u32_e32 v98, s25, v191
	global_store_dwordx4 v[106:107], v[102:105], off offset:256
	v_ashrrev_i32_e32 v99, 31, v98
	s_waitcnt vmcnt(2)
	v_mov_b64_e32 v[100:101], v[214:215]
	s_and_b64 vcc, exec, s[10:11]
	s_cbranch_vccnz .LBB0_206
	v_mov_b64_e32 v[58:59], v[224:225]
	v_mov_b64_e32 v[60:61], v[226:227]
	v_mov_b64_e32 v[70:71], v[228:229]
	v_mov_b64_e32 v[72:73], v[230:231]
	v_mov_b64_e32 v[42:43], v[232:233]
	v_mov_b64_e32 v[44:45], v[234:235]
	v_mov_b64_e32 v[54:55], v[236:237]
	v_mov_b64_e32 v[56:57], v[238:239]
	v_add_u32_e32 v240, 0x80, v184
	v_lshlrev_b32_e32 v240, 6, v240
	v_and_b32_e32 v240, 0x3f3c0, v240
	global_load_dwordx4 v[224:227], v240, s[38:39] offset:32
	global_load_dwordx4 v[228:231], v240, s[38:39] offset:48
	global_load_dwordx4 v[232:235], v240, s[38:39] offset:16
	global_load_dwordx4 v[236:239], v240, s[38:39]
	v_xor_b32_e32 v99, 0x80000000, v58
	v_xor_b32_e32 v102, 0x80000000, v59
	v_xor_b32_e32 v103, 0x80000000, v60
	v_xor_b32_e32 v104, 0x80000000, v61
	v_xor_b32_e32 v105, 0x80000000, v70
	v_xor_b32_e32 v106, 0x80000000, v71
	v_xor_b32_e32 v107, 0x80000000, v72
	v_xor_b32_e32 v108, 0x80000000, v73
	v_cndmask_b32_e64 v61, v61, v104, s[6:7]
	v_cndmask_b32_e64 v60, v60, v103, s[6:7]
	v_cndmask_b32_e64 v59, v59, v102, s[6:7]
	v_cndmask_b32_e64 v58, v58, v99, s[6:7]
	v_cndmask_b32_e64 v73, v73, v108, s[6:7]
	v_cndmask_b32_e64 v72, v72, v107, s[6:7]
	v_cndmask_b32_e64 v71, v71, v106, s[6:7]
	v_cndmask_b32_e64 v70, v70, v105, s[6:7]
.LBB0_206:
	v_ffbh_u32_e32 v99, v101
	v_min_u32_e32 v99, 32, v99
	v_lshlrev_b64 v[100:101], v99, v[100:101]
	v_min_u32_e32 v100, 1, v100
	v_or_b32_e32 v100, v101, v100
	v_cvt_f32_u32_e32 v100, v100
	v_sub_u32_e32 v99, 32, v99
	s_and_b64 vcc, exec, s[10:11]
	v_ldexp_f32 v99, v100, v99
	v_mul_f32_e32 v99, 0x37800000, v99
	v_fmamk_f32 v99, v99, 0x3a800000, v195
	v_rsq_f32_e32 v99, v99
	s_nop 0
	v_mul_f32_e32 v100, v185, v99
	v_pk_mul_f32 v[96:97], v[96:97], v[100:101] op_sel_hi:[1,0]
	v_pk_mul_f32 v[94:95], v[94:95], v[100:101] op_sel_hi:[1,0]
	v_pk_mul_f32 v[92:93], v[92:93], v[100:101] op_sel_hi:[1,0]
	v_pk_mul_f32 v[90:91], v[90:91], v[100:101] op_sel_hi:[1,0]
	s_cbranch_vccnz .LBB0_208
	v_mov_b32_e32 v99, v94
	v_mov_b32_e32 v101, v94
	s_nop 1
	v_permlane16_swap_b32_e32 v99, v101
	v_cndmask_b32_e64 v102, v99, v101, s[2:3]
	v_mov_b32_e32 v99, v95
	v_mov_b32_e32 v101, v95
	s_nop 1
	v_permlane16_swap_b32_e32 v99, v101
	v_cndmask_b32_e64 v103, v99, v101, s[2:3]
	v_mov_b32_e32 v99, v96
	v_mov_b32_e32 v101, v96
	s_nop 1
	v_permlane16_swap_b32_e32 v99, v101
	v_cndmask_b32_e64 v104, v99, v101, s[2:3]
	v_mov_b32_e32 v99, v97
	v_mov_b32_e32 v101, v97
	s_nop 1
	v_permlane16_swap_b32_e32 v99, v101
	v_cndmask_b32_e64 v105, v99, v101, s[2:3]
	v_mov_b32_e32 v99, v90
	v_mov_b32_e32 v101, v90
	s_nop 1
	v_permlane16_swap_b32_e32 v99, v101
	v_cndmask_b32_e64 v106, v99, v101, s[2:3]
	v_mov_b32_e32 v99, v91
	v_mov_b32_e32 v101, v91
	s_nop 1
	v_permlane16_swap_b32_e32 v99, v101
	v_cndmask_b32_e64 v107, v99, v101, s[2:3]
	v_mov_b32_e32 v99, v92
	v_mov_b32_e32 v101, v92
	s_nop 1
	v_permlane16_swap_b32_e32 v99, v101
	v_cndmask_b32_e64 v108, v99, v101, s[2:3]
	v_mov_b32_e32 v99, v93
	v_mov_b32_e32 v101, v93
	s_nop 1
	v_permlane16_swap_b32_e32 v99, v101
	v_cndmask_b32_e64 v109, v99, v101, s[2:3]
	v_pk_mul_f32 v[104:105], v[60:61], v[104:105]
	v_pk_mul_f32 v[102:103], v[58:59], v[102:103]
	v_pk_mul_f32 v[108:109], v[72:73], v[108:109]
	v_pk_mul_f32 v[106:107], v[70:71], v[106:107]
	v_pk_fma_f32 v[102:103], v[94:95], v[54:55], v[102:103]
	v_pk_fma_f32 v[104:105], v[96:97], v[56:57], v[104:105]
	v_pk_fma_f32 v[106:107], v[90:91], v[42:43], v[106:107]
	v_pk_fma_f32 v[108:109], v[92:93], v[44:45], v[108:109]
	v_cndmask_b32_e64 v97, v97, v105, s[4:5]
	v_cndmask_b32_e64 v96, v96, v104, s[4:5]
	v_cndmask_b32_e64 v95, v95, v103, s[4:5]
	v_cndmask_b32_e64 v94, v94, v102, s[4:5]
	v_cndmask_b32_e64 v93, v93, v109, s[4:5]
	v_cndmask_b32_e64 v92, v92, v108, s[4:5]
	v_cndmask_b32_e64 v91, v91, v107, s[4:5]
	v_cndmask_b32_e64 v90, v90, v106, s[4:5]

.LBB0_210:
	v_cvt_pk_bf16_f32 v86, v86, v87
	v_cvt_pk_bf16_f32 v87, v88, v89
	v_cvt_pk_bf16_f32 v88, v82, v83
	v_cvt_pk_bf16_f32 v89, v84, v85
	v_add_u32_e32 v82, 0x80, v184
	global_store_dwordx4 v[90:91], v[86:89], off offset:256
	v_ashrrev_i32_e32 v83, 31, v82
	s_waitcnt vmcnt(2)
	v_mov_b64_e32 v[84:85], v[216:217]
	s_and_b64 vcc, exec, s[10:11]
	s_cbranch_vccnz .LBB0_212
	v_mov_b64_e32 v[58:59], v[224:225]
	v_mov_b64_e32 v[60:61], v[226:227]
	v_mov_b64_e32 v[70:71], v[228:229]
	v_mov_b64_e32 v[72:73], v[230:231]
	v_mov_b64_e32 v[42:43], v[232:233]
	v_mov_b64_e32 v[44:45], v[234:235]
	v_mov_b64_e32 v[54:55], v[236:237]
	v_mov_b64_e32 v[56:57], v[238:239]
	v_add_u32_e32 v240, 0x90, v184
	v_lshlrev_b32_e32 v240, 6, v240
	v_and_b32_e32 v240, 0x3f7c0, v240
	global_load_dwordx4 v[224:227], v240, s[38:39] offset:32
	global_load_dwordx4 v[228:231], v240, s[38:39] offset:48
	global_load_dwordx4 v[232:235], v240, s[38:39] offset:16
	global_load_dwordx4 v[236:239], v240, s[38:39]
	v_xor_b32_e32 v83, 0x80000000, v58
	v_xor_b32_e32 v86, 0x80000000, v59
	v_xor_b32_e32 v87, 0x80000000, v60
	v_xor_b32_e32 v88, 0x80000000, v61
	v_xor_b32_e32 v89, 0x80000000, v70
	v_xor_b32_e32 v90, 0x80000000, v71
	v_xor_b32_e32 v91, 0x80000000, v72
	v_xor_b32_e32 v92, 0x80000000, v73
	v_cndmask_b32_e64 v61, v61, v88, s[6:7]
	v_cndmask_b32_e64 v60, v60, v87, s[6:7]
	v_cndmask_b32_e64 v59, v59, v86, s[6:7]
	v_cndmask_b32_e64 v58, v58, v83, s[6:7]
	v_cndmask_b32_e64 v73, v73, v92, s[6:7]
	v_cndmask_b32_e64 v72, v72, v91, s[6:7]
	v_cndmask_b32_e64 v71, v71, v90, s[6:7]
	v_cndmask_b32_e64 v70, v70, v89, s[6:7]
.LBB0_212:
	v_ffbh_u32_e32 v83, v85
	v_min_u32_e32 v83, 32, v83
	v_lshlrev_b64 v[84:85], v83, v[84:85]
	v_min_u32_e32 v84, 1, v84
	v_or_b32_e32 v84, v85, v84
	v_cvt_f32_u32_e32 v84, v84
	v_sub_u32_e32 v83, 32, v83
	s_and_b64 vcc, exec, s[10:11]
	v_ldexp_f32 v83, v84, v83
	v_mul_f32_e32 v83, 0x37800000, v83
	v_fmamk_f32 v83, v83, 0x3a800000, v195
	v_rsq_f32_e32 v83, v83
	s_nop 0
	v_mul_f32_e32 v84, v185, v83
	v_pk_mul_f32 v[80:81], v[80:81], v[84:85] op_sel_hi:[1,0]
	v_pk_mul_f32 v[78:79], v[78:79], v[84:85] op_sel_hi:[1,0]
	v_pk_mul_f32 v[76:77], v[76:77], v[84:85] op_sel_hi:[1,0]
	v_pk_mul_f32 v[74:75], v[74:75], v[84:85] op_sel_hi:[1,0]
	s_cbranch_vccnz .LBB0_214
	v_mov_b32_e32 v83, v78
	v_mov_b32_e32 v85, v78
	s_nop 1
	v_permlane16_swap_b32_e32 v83, v85
	v_cndmask_b32_e64 v86, v83, v85, s[2:3]
	v_mov_b32_e32 v83, v79
	v_mov_b32_e32 v85, v79
	s_nop 1
	v_permlane16_swap_b32_e32 v83, v85
	v_cndmask_b32_e64 v87, v83, v85, s[2:3]
	v_mov_b32_e32 v83, v80
	v_mov_b32_e32 v85, v80
	s_nop 1
	v_permlane16_swap_b32_e32 v83, v85
	v_cndmask_b32_e64 v88, v83, v85, s[2:3]
	v_mov_b32_e32 v83, v81
	v_mov_b32_e32 v85, v81
	s_nop 1
	v_permlane16_swap_b32_e32 v83, v85
	v_cndmask_b32_e64 v89, v83, v85, s[2:3]
	v_mov_b32_e32 v83, v74
	v_mov_b32_e32 v85, v74
	s_nop 1
	v_permlane16_swap_b32_e32 v83, v85
	v_cndmask_b32_e64 v90, v83, v85, s[2:3]
	v_mov_b32_e32 v83, v75
	v_mov_b32_e32 v85, v75
	s_nop 1
	v_permlane16_swap_b32_e32 v83, v85
	v_cndmask_b32_e64 v91, v83, v85, s[2:3]
	v_mov_b32_e32 v83, v76
	v_mov_b32_e32 v85, v76
	s_nop 1
	v_permlane16_swap_b32_e32 v83, v85
	v_cndmask_b32_e64 v92, v83, v85, s[2:3]
	v_mov_b32_e32 v83, v77
	v_mov_b32_e32 v85, v77
	s_nop 1
	v_permlane16_swap_b32_e32 v83, v85
	v_cndmask_b32_e64 v93, v83, v85, s[2:3]
	v_pk_mul_f32 v[88:89], v[60:61], v[88:89]
	v_pk_mul_f32 v[86:87], v[58:59], v[86:87]
	v_pk_mul_f32 v[92:93], v[72:73], v[92:93]
	v_pk_mul_f32 v[90:91], v[70:71], v[90:91]
	v_pk_fma_f32 v[86:87], v[78:79], v[54:55], v[86:87]
	v_pk_fma_f32 v[88:89], v[80:81], v[56:57], v[88:89]
	v_pk_fma_f32 v[90:91], v[74:75], v[42:43], v[90:91]
	v_pk_fma_f32 v[92:93], v[76:77], v[44:45], v[92:93]
	v_cndmask_b32_e64 v81, v81, v89, s[4:5]
	v_cndmask_b32_e64 v80, v80, v88, s[4:5]
	v_cndmask_b32_e64 v79, v79, v87, s[4:5]
	v_cndmask_b32_e64 v78, v78, v86, s[4:5]
	v_cndmask_b32_e64 v77, v77, v93, s[4:5]
	v_cndmask_b32_e64 v76, v76, v92, s[4:5]
	v_cndmask_b32_e64 v75, v75, v91, s[4:5]
	v_cndmask_b32_e64 v74, v74, v90, s[4:5]

.LBB0_216:
	v_cvt_pk_bf16_f32 v66, v66, v67
	v_cvt_pk_bf16_f32 v67, v68, v69
	v_cvt_pk_bf16_f32 v68, v62, v63
	v_cvt_pk_bf16_f32 v69, v64, v65
	v_add_u32_e32 v62, 0x90, v184
	global_store_dwordx4 v[74:75], v[66:69], off offset:256
	v_ashrrev_i32_e32 v63, 31, v62
	s_waitcnt vmcnt(2)
	v_mov_b64_e32 v[64:65], v[218:219]
	s_and_b64 vcc, exec, s[10:11]
	s_cbranch_vccnz .LBB0_218
	v_mov_b64_e32 v[58:59], v[224:225]
	v_mov_b64_e32 v[60:61], v[226:227]
	v_mov_b64_e32 v[66:67], v[228:229]
	v_mov_b64_e32 v[68:69], v[230:231]
	v_mov_b64_e32 v[42:43], v[232:233]
	v_mov_b64_e32 v[44:45], v[234:235]
	v_mov_b64_e32 v[54:55], v[236:237]
	v_mov_b64_e32 v[56:57], v[238:239]
	v_add_u32_e32 v240, 0xa0, v184
	v_lshlrev_b32_e32 v240, 6, v240
	v_and_b32_e32 v240, 0x3fbc0, v240
	global_load_dwordx4 v[224:227], v240, s[38:39] offset:32
	global_load_dwordx4 v[228:231], v240, s[38:39] offset:48
	global_load_dwordx4 v[232:235], v240, s[38:39] offset:16
	global_load_dwordx4 v[236:239], v240, s[38:39]
	v_xor_b32_e32 v63, 0x80000000, v58
	v_xor_b32_e32 v70, 0x80000000, v59
	v_xor_b32_e32 v71, 0x80000000, v60
	v_xor_b32_e32 v72, 0x80000000, v61
	v_xor_b32_e32 v74, 0x80000000, v66
	v_xor_b32_e32 v75, 0x80000000, v67
	v_xor_b32_e32 v76, 0x80000000, v68
	v_xor_b32_e32 v73, 0x80000000, v69
	v_cndmask_b32_e64 v61, v61, v72, s[6:7]
	v_cndmask_b32_e64 v60, v60, v71, s[6:7]
	v_cndmask_b32_e64 v59, v59, v70, s[6:7]
	v_cndmask_b32_e64 v58, v58, v63, s[6:7]
	v_cndmask_b32_e64 v73, v69, v73, s[6:7]
	v_cndmask_b32_e64 v72, v68, v76, s[6:7]
	v_cndmask_b32_e64 v71, v67, v75, s[6:7]
	v_cndmask_b32_e64 v70, v66, v74, s[6:7]
.LBB0_218:
	v_ffbh_u32_e32 v63, v65
	v_min_u32_e32 v63, 32, v63
	v_lshlrev_b64 v[64:65], v63, v[64:65]
	v_min_u32_e32 v64, 1, v64
	v_or_b32_e32 v64, v65, v64
	v_cvt_f32_u32_e32 v64, v64
	v_sub_u32_e32 v63, 32, v63
	s_and_b64 vcc, exec, s[10:11]
	v_ldexp_f32 v63, v64, v63
	v_mul_f32_e32 v63, 0x37800000, v63
	v_fmamk_f32 v63, v63, 0x3a800000, v195
	v_rsq_f32_e32 v63, v63
	s_nop 0
	v_mul_f32_e32 v64, v185, v63
	v_pk_mul_f32 v[52:53], v[52:53], v[64:65] op_sel_hi:[1,0]
	v_pk_mul_f32 v[50:51], v[50:51], v[64:65] op_sel_hi:[1,0]
	v_pk_mul_f32 v[48:49], v[48:49], v[64:65] op_sel_hi:[1,0]
	v_pk_mul_f32 v[46:47], v[46:47], v[64:65] op_sel_hi:[1,0]
	s_cbranch_vccnz .LBB0_220
	v_mov_b32_e32 v63, v50
	v_mov_b32_e32 v65, v50
	s_nop 1
	v_permlane16_swap_b32_e32 v63, v65
	v_cndmask_b32_e64 v66, v63, v65, s[2:3]
	v_mov_b32_e32 v63, v51
	v_mov_b32_e32 v65, v51
	s_nop 1
	v_permlane16_swap_b32_e32 v63, v65
	v_cndmask_b32_e64 v67, v63, v65, s[2:3]
	v_mov_b32_e32 v63, v52
	v_mov_b32_e32 v65, v52
	s_nop 1
	v_permlane16_swap_b32_e32 v63, v65
	v_cndmask_b32_e64 v68, v63, v65, s[2:3]
	v_mov_b32_e32 v63, v53
	v_mov_b32_e32 v65, v53
	s_nop 1
	v_permlane16_swap_b32_e32 v63, v65
	v_cndmask_b32_e64 v69, v63, v65, s[2:3]
	v_mov_b32_e32 v63, v46
	v_mov_b32_e32 v65, v46
	s_nop 1
	v_permlane16_swap_b32_e32 v63, v65
	v_cndmask_b32_e64 v74, v63, v65, s[2:3]
	v_mov_b32_e32 v63, v47
	v_mov_b32_e32 v65, v47
	s_nop 1
	v_permlane16_swap_b32_e32 v63, v65
	v_cndmask_b32_e64 v75, v63, v65, s[2:3]
	v_mov_b32_e32 v63, v48
	v_mov_b32_e32 v65, v48
	s_nop 1
	v_permlane16_swap_b32_e32 v63, v65
	v_cndmask_b32_e64 v76, v63, v65, s[2:3]
	v_mov_b32_e32 v63, v49
	v_mov_b32_e32 v65, v49
	s_nop 1
	v_permlane16_swap_b32_e32 v63, v65
	v_cndmask_b32_e64 v77, v63, v65, s[2:3]
	v_pk_mul_f32 v[68:69], v[60:61], v[68:69]
	v_pk_mul_f32 v[66:67], v[58:59], v[66:67]
	v_pk_mul_f32 v[76:77], v[72:73], v[76:77]
	v_pk_mul_f32 v[74:75], v[70:71], v[74:75]
	v_pk_fma_f32 v[66:67], v[50:51], v[54:55], v[66:67]
	v_pk_fma_f32 v[68:69], v[52:53], v[56:57], v[68:69]
	v_pk_fma_f32 v[74:75], v[46:47], v[42:43], v[74:75]
	v_pk_fma_f32 v[76:77], v[48:49], v[44:45], v[76:77]
	v_cndmask_b32_e64 v53, v53, v69, s[4:5]
	v_cndmask_b32_e64 v52, v52, v68, s[4:5]
	v_cndmask_b32_e64 v51, v51, v67, s[4:5]
	v_cndmask_b32_e64 v50, v50, v66, s[4:5]
	v_cndmask_b32_e64 v49, v49, v77, s[4:5]
	v_cndmask_b32_e64 v48, v48, v76, s[4:5]
	v_cndmask_b32_e64 v47, v47, v75, s[4:5]
	v_cndmask_b32_e64 v46, v46, v74, s[4:5]

.LBB0_222:
	v_cvt_pk_bf16_f32 v38, v38, v39
	v_cvt_pk_bf16_f32 v39, v40, v41
	v_cvt_pk_bf16_f32 v40, v34, v35
	v_cvt_pk_bf16_f32 v41, v36, v37
	v_add_u32_e32 v34, 0xa0, v184
	global_store_dwordx4 v[46:47], v[38:41], off offset:256
	v_ashrrev_i32_e32 v35, 31, v34
	s_waitcnt vmcnt(2)
	v_mov_b64_e32 v[36:37], v[220:221]
	s_and_b64 vcc, exec, s[10:11]
	s_cbranch_vccnz .LBB0_224
	v_mov_b64_e32 v[38:39], v[224:225]
	v_mov_b64_e32 v[40:41], v[226:227]
	v_mov_b64_e32 v[46:47], v[228:229]
	v_mov_b64_e32 v[48:49], v[230:231]
	v_mov_b64_e32 v[42:43], v[232:233]
	v_mov_b64_e32 v[44:45], v[234:235]
	v_mov_b64_e32 v[54:55], v[236:237]
	v_mov_b64_e32 v[56:57], v[238:239]
	v_add_u32_e32 v240, 0xb0, v184
	v_lshlrev_b32_e32 v240, 6, v240
	v_and_b32_e32 v240, 0x3ffc0, v240
	global_load_dwordx4 v[224:227], v240, s[38:39] offset:32
	global_load_dwordx4 v[228:231], v240, s[38:39] offset:48
	global_load_dwordx4 v[232:235], v240, s[38:39] offset:16
	global_load_dwordx4 v[236:239], v240, s[38:39]
	v_xor_b32_e32 v35, 0x80000000, v38
	v_xor_b32_e32 v50, 0x80000000, v39
	v_xor_b32_e32 v51, 0x80000000, v40
	v_xor_b32_e32 v52, 0x80000000, v41
	v_xor_b32_e32 v53, 0x80000000, v46
	v_xor_b32_e32 v62, 0x80000000, v47
	v_xor_b32_e32 v63, 0x80000000, v48
	v_xor_b32_e32 v64, 0x80000000, v49
	v_cndmask_b32_e64 v61, v41, v52, s[6:7]
	v_cndmask_b32_e64 v60, v40, v51, s[6:7]
	v_cndmask_b32_e64 v59, v39, v50, s[6:7]
	v_cndmask_b32_e64 v58, v38, v35, s[6:7]
	v_cndmask_b32_e64 v73, v49, v64, s[6:7]
	v_cndmask_b32_e64 v72, v48, v63, s[6:7]
	v_cndmask_b32_e64 v71, v47, v62, s[6:7]
	v_cndmask_b32_e64 v70, v46, v53, s[6:7]
.LBB0_224:
	v_ffbh_u32_e32 v35, v37
	v_min_u32_e32 v35, 32, v35
	v_lshlrev_b64 v[36:37], v35, v[36:37]
	v_min_u32_e32 v36, 1, v36
	v_or_b32_e32 v36, v37, v36
	v_cvt_f32_u32_e32 v36, v36
	v_sub_u32_e32 v35, 32, v35
	s_and_b64 vcc, exec, s[10:11]
	v_ldexp_f32 v35, v36, v35
	v_mul_f32_e32 v35, 0x37800000, v35
	v_fmamk_f32 v35, v35, 0x3a800000, v195
	v_rsq_f32_e32 v35, v35
	s_nop 0
	v_mul_f32_e32 v36, v185, v35
	v_pk_mul_f32 v[32:33], v[32:33], v[36:37] op_sel_hi:[1,0]
	v_pk_mul_f32 v[30:31], v[30:31], v[36:37] op_sel_hi:[1,0]
	v_pk_mul_f32 v[28:29], v[28:29], v[36:37] op_sel_hi:[1,0]
	v_pk_mul_f32 v[26:27], v[26:27], v[36:37] op_sel_hi:[1,0]
	s_cbranch_vccnz .LBB0_226
	v_mov_b32_e32 v35, v30
	v_mov_b32_e32 v37, v30
	s_nop 1
	v_permlane16_swap_b32_e32 v35, v37
	v_cndmask_b32_e64 v38, v35, v37, s[2:3]
	v_mov_b32_e32 v35, v31
	v_mov_b32_e32 v37, v31
	s_nop 1
	v_permlane16_swap_b32_e32 v35, v37
	v_cndmask_b32_e64 v39, v35, v37, s[2:3]
	v_mov_b32_e32 v35, v32
	v_mov_b32_e32 v37, v32
	s_nop 1
	v_permlane16_swap_b32_e32 v35, v37
	v_cndmask_b32_e64 v40, v35, v37, s[2:3]
	v_mov_b32_e32 v35, v33
	v_mov_b32_e32 v37, v33
	s_nop 1
	v_permlane16_swap_b32_e32 v35, v37
	v_cndmask_b32_e64 v41, v35, v37, s[2:3]
	v_mov_b32_e32 v35, v26
	v_mov_b32_e32 v37, v26
	s_nop 1
	v_permlane16_swap_b32_e32 v35, v37
	v_cndmask_b32_e64 v46, v35, v37, s[2:3]
	v_mov_b32_e32 v35, v27
	v_mov_b32_e32 v37, v27
	s_nop 1
	v_permlane16_swap_b32_e32 v35, v37
	v_cndmask_b32_e64 v47, v35, v37, s[2:3]
	v_mov_b32_e32 v35, v28
	v_mov_b32_e32 v37, v28
	s_nop 1
	v_permlane16_swap_b32_e32 v35, v37
	v_cndmask_b32_e64 v48, v35, v37, s[2:3]
	v_mov_b32_e32 v35, v29
	v_mov_b32_e32 v37, v29
	s_nop 1
	v_permlane16_swap_b32_e32 v35, v37
	v_cndmask_b32_e64 v49, v35, v37, s[2:3]
	v_pk_mul_f32 v[40:41], v[60:61], v[40:41]
	v_pk_mul_f32 v[38:39], v[58:59], v[38:39]
	v_pk_mul_f32 v[48:49], v[72:73], v[48:49]
	v_pk_mul_f32 v[46:47], v[70:71], v[46:47]
	v_pk_fma_f32 v[38:39], v[30:31], v[54:55], v[38:39]
	v_pk_fma_f32 v[40:41], v[32:33], v[56:57], v[40:41]
	v_pk_fma_f32 v[46:47], v[26:27], v[42:43], v[46:47]
	v_pk_fma_f32 v[48:49], v[28:29], v[44:45], v[48:49]
	v_cndmask_b32_e64 v33, v33, v41, s[4:5]
	v_cndmask_b32_e64 v32, v32, v40, s[4:5]
	v_cndmask_b32_e64 v31, v31, v39, s[4:5]
	v_cndmask_b32_e64 v30, v30, v38, s[4:5]
	v_cndmask_b32_e64 v29, v29, v49, s[4:5]
	v_cndmask_b32_e64 v28, v28, v48, s[4:5]
	v_cndmask_b32_e64 v27, v27, v47, s[4:5]
	v_cndmask_b32_e64 v26, v26, v46, s[4:5]

.LBB0_228:
	v_cvt_pk_bf16_f32 v22, v22, v23
	v_cvt_pk_bf16_f32 v23, v24, v25
	v_cvt_pk_bf16_f32 v24, v18, v19
	v_cvt_pk_bf16_f32 v25, v20, v21
	v_add_u32_e32 v18, 0xb0, v184
	global_store_dwordx4 v[26:27], v[22:25], off offset:256
	v_ashrrev_i32_e32 v19, 31, v18
	s_waitcnt vmcnt(2)
	v_mov_b64_e32 v[20:21], v[222:223]
	s_and_b64 vcc, exec, s[10:11]
	s_cbranch_vccnz .LBB0_230
	v_mov_b64_e32 v[22:23], v[224:225]
	v_mov_b64_e32 v[24:25], v[226:227]
	v_mov_b64_e32 v[26:27], v[228:229]
	v_mov_b64_e32 v[28:29], v[230:231]
	v_mov_b64_e32 v[42:43], v[232:233]
	v_mov_b64_e32 v[44:45], v[234:235]
	v_mov_b64_e32 v[54:55], v[236:237]
	v_mov_b64_e32 v[56:57], v[238:239]
	v_xor_b32_e32 v19, 0x80000000, v22
	v_xor_b32_e32 v30, 0x80000000, v23
	v_xor_b32_e32 v31, 0x80000000, v24
	v_xor_b32_e32 v32, 0x80000000, v25
	v_xor_b32_e32 v33, 0x80000000, v26
	v_xor_b32_e32 v34, 0x80000000, v27
	v_xor_b32_e32 v35, 0x80000000, v28
	v_xor_b32_e32 v36, 0x80000000, v29
	v_cndmask_b32_e64 v61, v25, v32, s[6:7]
	v_cndmask_b32_e64 v60, v24, v31, s[6:7]
	v_cndmask_b32_e64 v59, v23, v30, s[6:7]
	v_cndmask_b32_e64 v58, v22, v19, s[6:7]
	v_cndmask_b32_e64 v73, v29, v36, s[6:7]
	v_cndmask_b32_e64 v72, v28, v35, s[6:7]
	v_cndmask_b32_e64 v71, v27, v34, s[6:7]
	v_cndmask_b32_e64 v70, v26, v33, s[6:7]
.LBB0_230:
	v_ffbh_u32_e32 v19, v21
	v_min_u32_e32 v19, 32, v19
	v_lshlrev_b64 v[20:21], v19, v[20:21]
	v_min_u32_e32 v20, 1, v20
	v_or_b32_e32 v20, v21, v20
	v_cvt_f32_u32_e32 v20, v20
	v_sub_u32_e32 v19, 32, v19
	s_and_b64 vcc, exec, s[10:11]
	v_ldexp_f32 v19, v20, v19
	v_mul_f32_e32 v19, 0x37800000, v19
	v_fmamk_f32 v19, v19, 0x3a800000, v195
	v_rsq_f32_e32 v19, v19
	s_nop 0
	v_mul_f32_e32 v20, v185, v19
	v_pk_mul_f32 v[16:17], v[16:17], v[20:21] op_sel_hi:[1,0]
	v_pk_mul_f32 v[14:15], v[14:15], v[20:21] op_sel_hi:[1,0]
	v_pk_mul_f32 v[12:13], v[12:13], v[20:21] op_sel_hi:[1,0]
	v_pk_mul_f32 v[10:11], v[10:11], v[20:21] op_sel_hi:[1,0]
	s_cbranch_vccnz .LBB0_232
	v_mov_b32_e32 v19, v14
	v_mov_b32_e32 v21, v14
	s_nop 1
	v_permlane16_swap_b32_e32 v19, v21
	v_cndmask_b32_e64 v22, v19, v21, s[2:3]
	v_mov_b32_e32 v19, v15
	v_mov_b32_e32 v21, v15
	s_nop 1
	v_permlane16_swap_b32_e32 v19, v21
	v_cndmask_b32_e64 v23, v19, v21, s[2:3]
	v_mov_b32_e32 v19, v16
	v_mov_b32_e32 v21, v16
	s_nop 1
	v_permlane16_swap_b32_e32 v19, v21
	v_cndmask_b32_e64 v24, v19, v21, s[2:3]
	v_mov_b32_e32 v19, v17
	v_mov_b32_e32 v21, v17
	s_nop 1
	v_permlane16_swap_b32_e32 v19, v21
	v_cndmask_b32_e64 v25, v19, v21, s[2:3]
	v_mov_b32_e32 v19, v10
	v_mov_b32_e32 v21, v10
	s_nop 1
	v_permlane16_swap_b32_e32 v19, v21
	v_cndmask_b32_e64 v26, v19, v21, s[2:3]
	v_mov_b32_e32 v19, v11
	v_mov_b32_e32 v21, v11
	s_nop 1
	v_permlane16_swap_b32_e32 v19, v21
	v_cndmask_b32_e64 v27, v19, v21, s[2:3]
	v_mov_b32_e32 v19, v12
	v_mov_b32_e32 v21, v12
	s_nop 1
	v_permlane16_swap_b32_e32 v19, v21
	v_cndmask_b32_e64 v28, v19, v21, s[2:3]
	v_mov_b32_e32 v19, v13
	v_mov_b32_e32 v21, v13
	s_nop 1
	v_permlane16_swap_b32_e32 v19, v21
	v_cndmask_b32_e64 v29, v19, v21, s[2:3]
	v_pk_mul_f32 v[24:25], v[60:61], v[24:25]
	v_pk_mul_f32 v[22:23], v[58:59], v[22:23]
	v_pk_mul_f32 v[28:29], v[72:73], v[28:29]
	v_pk_mul_f32 v[26:27], v[70:71], v[26:27]
	v_pk_fma_f32 v[22:23], v[14:15], v[54:55], v[22:23]
	v_pk_fma_f32 v[24:25], v[16:17], v[56:57], v[24:25]
	v_pk_fma_f32 v[26:27], v[10:11], v[42:43], v[26:27]
	v_pk_fma_f32 v[28:29], v[12:13], v[44:45], v[28:29]
	v_cndmask_b32_e64 v17, v17, v25, s[4:5]
	v_cndmask_b32_e64 v16, v16, v24, s[4:5]
	v_cndmask_b32_e64 v15, v15, v23, s[4:5]
	v_cndmask_b32_e64 v14, v14, v22, s[4:5]
	v_cndmask_b32_e64 v13, v13, v29, s[4:5]
	v_cndmask_b32_e64 v12, v12, v28, s[4:5]
	v_cndmask_b32_e64 v11, v11, v27, s[4:5]
	v_cndmask_b32_e64 v10, v10, v26, s[4:5]
